# S4 Hyena transpose pass software-pipelined: next tile's loads issued before current tile's LDS transpose/stores (two register sets)
# baseline (speedup 1.0000x reference)
; DI u32 pack2(float a, float b) { return (u32)f2bf(a) | ((u32)f2bf(b) << 16); }
; DI float bflo(u32 v) { return __uint_as_float(v << 16); }
; DI float bfhi(u32 v) { return __uint_as_float(v & 0xffff0000u); }
; DI float silu_f(float x) { return x / (1.f + __expf(-x)); }
; DI void phase_ssd_combine(const Params& p, int l, int bid, int nblk) {
;     ...
;   for (int row = bid * 4 + w; row < ROWS; row += nblk * 4) {
;     const int pos = row % TPB;
;     if (l == 1 && pos < CTXL) continue;
;     const uint4 vf = *(const uint4*)(YF + (size_t)row * 512 + c0);
;     const uint4 vb = *(const uint4*)(YB + (size_t)row * 512 + c0);
;     const uint4 vx = *(const uint4*)(XBCA + (size_t)row * 1024 + c0);
;     const uint4 vz = *(const uint4*)(PZ + (size_t)row * 512 + c0);
;     const u32 af_[4] = {vf.x, vf.y, vf.z, vf.w}, ab_[4] = {vb.x, vb.y, vb.z, vb.w};
;     const u32 ax_[4] = {vx.x, vx.y, vx.z, vx.w}, az_[4] = {vz.x, vz.y, vz.z, vz.w};
;     float y[8];
;     float ss = 0.f;
; #pragma unroll
;     for (int i = 0; i < 4; ++i) {
;       const float y0 = bflo(af_[i]) + bflo(ab_[i]) + dsk * bflo(ax_[i]);
;       const float y1 = bfhi(af_[i]) + bfhi(ab_[i]) + dsk * bfhi(ax_[i]);
;       y[2 * i] = y0 * silu_f(bflo(az_[i]));
;       y[2 * i + 1] = y1 * silu_f(bfhi(az_[i]));
;       ss += y[2 * i] * y[2 * i] + y[2 * i + 1] * y[2 * i + 1];
;     }
; #pragma unroll
;     for (int o = 16; o >= 1; o >>= 1) ss += __shfl_xor(ss, o);
;     const float rs = rsqrtf(ss * (1.f / 256.f) + EPSF);
;     float o8[8];
; #pragma unroll
;     for (int i = 0; i < 8; ++i) o8[i] = y[i] * rs * ng[c0 + i];
;     uint4 o = {pack2(o8[0], o8[1]), pack2(o8[2], o8[3]), pack2(o8[4], o8[5]), pack2(o8[6], o8[7])};
;     *(uint4*)&YM[(size_t)row * 1024 + 256 + c0] = o;
;   }
.Lcmb_top:
	s_waitcnt vmcnt(5)
	v_lshlrev_b32_e32 v64, 16, v32
	v_and_b32_e32 v65, 0xffff0000, v32
	v_lshlrev_b32_e32 v66, 16, v33
	v_and_b32_e32 v67, 0xffff0000, v33
	v_lshlrev_b32_e32 v68, 16, v34
	v_and_b32_e32 v69, 0xffff0000, v34
	v_lshlrev_b32_e32 v70, 16, v35
	v_and_b32_e32 v71, 0xffff0000, v35
	v_lshlrev_b32_e32 v80, 16, v36
	v_and_b32_e32 v81, 0xffff0000, v36
	v_lshlrev_b32_e32 v82, 16, v37
	v_and_b32_e32 v83, 0xffff0000, v37
	v_lshlrev_b32_e32 v84, 16, v38
	v_and_b32_e32 v85, 0xffff0000, v38
	v_lshlrev_b32_e32 v86, 16, v39
	v_and_b32_e32 v87, 0xffff0000, v39
	v_add_f32_e32 v64, v64, v80
	v_add_f32_e32 v65, v65, v81
	v_add_f32_e32 v66, v66, v82
	v_add_f32_e32 v67, v67, v83
	v_add_f32_e32 v68, v68, v84
	v_add_f32_e32 v69, v69, v85
	v_add_f32_e32 v70, v70, v86
	v_add_f32_e32 v71, v71, v87
	v_lshlrev_b32_e32 v80, 16, v40
	v_and_b32_e32 v81, 0xffff0000, v40
	v_lshlrev_b32_e32 v82, 16, v41
	v_and_b32_e32 v83, 0xffff0000, v41
	v_lshlrev_b32_e32 v84, 16, v42
	v_and_b32_e32 v85, 0xffff0000, v42
	v_lshlrev_b32_e32 v86, 16, v43
	v_and_b32_e32 v87, 0xffff0000, v43
	v_fmac_f32_e32 v64, v24, v80
	v_fmac_f32_e32 v65, v24, v81
	v_fmac_f32_e32 v66, v24, v82
	v_fmac_f32_e32 v67, v24, v83
	v_fmac_f32_e32 v68, v24, v84
	v_fmac_f32_e32 v69, v24, v85
	v_fmac_f32_e32 v70, v24, v86
	v_fmac_f32_e32 v71, v24, v87
	v_lshlrev_b32_e32 v72, 16, v44
	v_and_b32_e32 v73, 0xffff0000, v44
	v_lshlrev_b32_e32 v74, 16, v45
	v_and_b32_e32 v75, 0xffff0000, v45
	v_lshlrev_b32_e32 v76, 16, v46
	v_and_b32_e32 v77, 0xffff0000, v46
	v_lshlrev_b32_e32 v78, 16, v47
	v_and_b32_e32 v79, 0xffff0000, v47
	v_mul_f32_e32 v80, 0xbfb8aa3b, v72
	v_mul_f32_e32 v81, 0xbfb8aa3b, v73
	v_mul_f32_e32 v82, 0xbfb8aa3b, v74
	v_mul_f32_e32 v83, 0xbfb8aa3b, v75
	v_mul_f32_e32 v84, 0xbfb8aa3b, v76
	v_mul_f32_e32 v85, 0xbfb8aa3b, v77
	v_mul_f32_e32 v86, 0xbfb8aa3b, v78
	v_mul_f32_e32 v87, 0xbfb8aa3b, v79
	v_exp_f32_e32 v80, v80
	v_exp_f32_e32 v81, v81
	v_exp_f32_e32 v82, v82
	v_exp_f32_e32 v83, v83
	v_exp_f32_e32 v84, v84
	v_exp_f32_e32 v85, v85
	v_exp_f32_e32 v86, v86
	v_exp_f32_e32 v87, v87
	v_add_f32_e32 v80, 1.0, v80
	v_add_f32_e32 v81, 1.0, v81
	v_add_f32_e32 v82, 1.0, v82
	v_add_f32_e32 v83, 1.0, v83
	v_add_f32_e32 v84, 1.0, v84
	v_add_f32_e32 v85, 1.0, v85
	v_add_f32_e32 v86, 1.0, v86
	v_add_f32_e32 v87, 1.0, v87
	v_rcp_f32_e32 v80, v80
	v_rcp_f32_e32 v81, v81
	v_rcp_f32_e32 v82, v82
	v_rcp_f32_e32 v83, v83
	v_rcp_f32_e32 v84, v84
	v_rcp_f32_e32 v85, v85
	v_rcp_f32_e32 v86, v86
	v_rcp_f32_e32 v87, v87
	v_mul_f32_e32 v72, v72, v80
	v_mul_f32_e32 v73, v73, v81
	v_mul_f32_e32 v74, v74, v82
	v_mul_f32_e32 v75, v75, v83
	v_mul_f32_e32 v76, v76, v84
	v_mul_f32_e32 v77, v77, v85
	v_mul_f32_e32 v78, v78, v86
	v_mul_f32_e32 v79, v79, v87
	v_mul_f32_e32 v64, v64, v72
	v_mul_f32_e32 v65, v65, v73
	v_mul_f32_e32 v66, v66, v74
	v_mul_f32_e32 v67, v67, v75
	v_mul_f32_e32 v68, v68, v76
	v_mul_f32_e32 v69, v69, v77
	v_mul_f32_e32 v70, v70, v78
	v_mul_f32_e32 v71, v71, v79
	v_mul_f32_e32 v7, v64, v64
	v_fmac_f32_e32 v7, v65, v65
	v_fmac_f32_e32 v7, v66, v66
	v_fmac_f32_e32 v7, v67, v67
	v_fmac_f32_e32 v7, v68, v68
	v_fmac_f32_e32 v7, v69, v69
	v_fmac_f32_e32 v7, v70, v70
	v_fmac_f32_e32 v7, v71, v71
	s_nop 1
	v_add_f32_dpp v7, v7, v7 quad_perm:[1,0,3,2] row_mask:0xf bank_mask:0xf
	s_nop 1
	v_add_f32_dpp v7, v7, v7 quad_perm:[2,3,0,1] row_mask:0xf bank_mask:0xf
	s_nop 1
	v_add_f32_dpp v7, v7, v7 row_half_mirror row_mask:0xf bank_mask:0xf
	s_nop 1
	v_add_f32_dpp v7, v7, v7 row_mirror row_mask:0xf bank_mask:0xf
	s_nop 1
	ds_bpermute_b32 v8, v5, v7
	s_waitcnt lgkmcnt(0)
	v_add_f32_e32 v7, v7, v8
	v_mov_b32_e32 v8, 0x358637bd
	v_fmac_f32_e32 v8, 0x3b800000, v7
	v_rsq_f32_e32 v8, v8
	s_nop 0
	v_mul_f32_e32 v64, v64, v8
	v_mul_f32_e32 v65, v65, v8
	v_mul_f32_e32 v66, v66, v8
	v_mul_f32_e32 v67, v67, v8
	v_mul_f32_e32 v68, v68, v8
	v_mul_f32_e32 v69, v69, v8
	v_mul_f32_e32 v70, v70, v8
	v_mul_f32_e32 v71, v71, v8
	v_mul_f32_e32 v64, v64, v16
	v_mul_f32_e32 v65, v65, v17
	v_mul_f32_e32 v66, v66, v18
	v_mul_f32_e32 v67, v67, v19
	v_mul_f32_e32 v68, v68, v20
	v_mul_f32_e32 v69, v69, v21
	v_mul_f32_e32 v70, v70, v22
	v_mul_f32_e32 v71, v71, v23
	v_cvt_pk_bf16_f32 v88, v64, v65
	v_cvt_pk_bf16_f32 v89, v66, v67
	v_cvt_pk_bf16_f32 v90, v68, v69
	v_cvt_pk_bf16_f32 v91, v70, v71
	s_nop 0
	global_store_dwordx4 v4, v[88:91], s[80:81] offset:512
	s_add_i32 s28, s27, 2
	s_cmp_lt_u32 s28, s26
	s_cselect_b32 s28, s28, 0
	s_cmp_ge_u32 s28, s23
	s_addc_u32 s44, s28, 0
	s_cmp_ge_u32 s44, s25
	s_addc_u32 s44, s44, 0
	s_lshl_b32 s44, s44, 11
	s_add_i32 s44, s44, s19
	s_lshl_b32 s16, s44, 10
	s_lshl_b32 s17, s44, 11
	s_add_u32 s30, s96, s16
	s_addc_u32 s31, s97, 0
	s_add_u32 s48, s30, 0x3600000
	s_addc_u32 s49, s31, 0
	s_add_u32 s30, s30, 0x5a00000
	s_addc_u32 s31, s31, 0
	s_add_u32 s38, s30, 0x2400000
	s_addc_u32 s39, s31, 0
	s_add_u32 s66, s96, s17
	s_addc_u32 s67, s97, 0
	s_add_u32 s66, s66, 0xea00000
	s_addc_u32 s67, s67, 0
	s_add_u32 s80, s6, s17
	s_addc_u32 s81, s7, 0
	global_load_dwordx4 v[32:35], v4, s[30:31]
	global_load_dwordx4 v[36:39], v4, s[38:39]
	global_load_dwordx4 v[40:43], v4, s[66:67]
	global_load_dwordx4 v[44:47], v4, s[48:49]
	s_waitcnt vmcnt(5)
; DI u32 pack2(float a, float b) { return (u32)f2bf(a) | ((u32)f2bf(b) << 16); }
; DI float bflo(u32 v) { return __uint_as_float(v << 16); }
; DI float bfhi(u32 v) { return __uint_as_float(v & 0xffff0000u); }
; DI float silu_f(float x) { return x / (1.f + __expf(-x)); }
; DI void phase_ssd_combine(const Params& p, int l, int bid, int nblk) {
;     ...
;   for (int row = bid * 4 + w; row < ROWS; row += nblk * 4) {
;     const int pos = row % TPB;
;     if (l == 1 && pos < CTXL) continue;
;     const uint4 vf = *(const uint4*)(YF + (size_t)row * 512 + c0);
;     const uint4 vb = *(const uint4*)(YB + (size_t)row * 512 + c0);
;     const uint4 vx = *(const uint4*)(XBCA + (size_t)row * 1024 + c0);
;     const uint4 vz = *(const uint4*)(PZ + (size_t)row * 512 + c0);
;     const u32 af_[4] = {vf.x, vf.y, vf.z, vf.w}, ab_[4] = {vb.x, vb.y, vb.z, vb.w};
;     const u32 ax_[4] = {vx.x, vx.y, vx.z, vx.w}, az_[4] = {vz.x, vz.y, vz.z, vz.w};
;     float y[8];
;     float ss = 0.f;
; #pragma unroll
;     for (int i = 0; i < 4; ++i) {
;       const float y0 = bflo(af_[i]) + bflo(ab_[i]) + dsk * bflo(ax_[i]);
;       const float y1 = bfhi(af_[i]) + bfhi(ab_[i]) + dsk * bfhi(ax_[i]);
;       y[2 * i] = y0 * silu_f(bflo(az_[i]));
;       y[2 * i + 1] = y1 * silu_f(bfhi(az_[i]));
;       ss += y[2 * i] * y[2 * i] + y[2 * i + 1] * y[2 * i + 1];
;     }
; #pragma unroll
;     for (int o = 16; o >= 1; o >>= 1) ss += __shfl_xor(ss, o);
;     const float rs = rsqrtf(ss * (1.f / 256.f) + EPSF);
;     float o8[8];
; #pragma unroll
;     for (int i = 0; i < 8; ++i) o8[i] = y[i] * rs * ng[c0 + i];
;     uint4 o = {pack2(o8[0], o8[1]), pack2(o8[2], o8[3]), pack2(o8[4], o8[5]), pack2(o8[6], o8[7])};
;     *(uint4*)&YM[(size_t)row * 1024 + 256 + c0] = o;
;   }
	v_lshlrev_b32_e32 v64, 16, v48
	v_and_b32_e32 v65, 0xffff0000, v48
	v_lshlrev_b32_e32 v66, 16, v49
	v_and_b32_e32 v67, 0xffff0000, v49
	v_lshlrev_b32_e32 v68, 16, v50
	v_and_b32_e32 v69, 0xffff0000, v50
	v_lshlrev_b32_e32 v70, 16, v51
	v_and_b32_e32 v71, 0xffff0000, v51
	v_lshlrev_b32_e32 v80, 16, v52
	v_and_b32_e32 v81, 0xffff0000, v52
	v_lshlrev_b32_e32 v82, 16, v53
	v_and_b32_e32 v83, 0xffff0000, v53
	v_lshlrev_b32_e32 v84, 16, v54
	v_and_b32_e32 v85, 0xffff0000, v54
	v_lshlrev_b32_e32 v86, 16, v55
	v_and_b32_e32 v87, 0xffff0000, v55
	v_add_f32_e32 v64, v64, v80
	v_add_f32_e32 v65, v65, v81
	v_add_f32_e32 v66, v66, v82
	v_add_f32_e32 v67, v67, v83
	v_add_f32_e32 v68, v68, v84
	v_add_f32_e32 v69, v69, v85
	v_add_f32_e32 v70, v70, v86
	v_add_f32_e32 v71, v71, v87
	v_lshlrev_b32_e32 v80, 16, v56
	v_and_b32_e32 v81, 0xffff0000, v56
	v_lshlrev_b32_e32 v82, 16, v57
	v_and_b32_e32 v83, 0xffff0000, v57
	v_lshlrev_b32_e32 v84, 16, v58
	v_and_b32_e32 v85, 0xffff0000, v58
	v_lshlrev_b32_e32 v86, 16, v59
	v_and_b32_e32 v87, 0xffff0000, v59
	v_fmac_f32_e32 v64, v24, v80
	v_fmac_f32_e32 v65, v24, v81
	v_fmac_f32_e32 v66, v24, v82
	v_fmac_f32_e32 v67, v24, v83
	v_fmac_f32_e32 v68, v24, v84
	v_fmac_f32_e32 v69, v24, v85
	v_fmac_f32_e32 v70, v24, v86
	v_fmac_f32_e32 v71, v24, v87
	v_lshlrev_b32_e32 v72, 16, v60
	v_and_b32_e32 v73, 0xffff0000, v60
	v_lshlrev_b32_e32 v74, 16, v61
	v_and_b32_e32 v75, 0xffff0000, v61
	v_lshlrev_b32_e32 v76, 16, v62
	v_and_b32_e32 v77, 0xffff0000, v62
	v_lshlrev_b32_e32 v78, 16, v63
	v_and_b32_e32 v79, 0xffff0000, v63
	v_mul_f32_e32 v80, 0xbfb8aa3b, v72
	v_mul_f32_e32 v81, 0xbfb8aa3b, v73
	v_mul_f32_e32 v82, 0xbfb8aa3b, v74
	v_mul_f32_e32 v83, 0xbfb8aa3b, v75
	v_mul_f32_e32 v84, 0xbfb8aa3b, v76
	v_mul_f32_e32 v85, 0xbfb8aa3b, v77
	v_mul_f32_e32 v86, 0xbfb8aa3b, v78
	v_mul_f32_e32 v87, 0xbfb8aa3b, v79
	v_exp_f32_e32 v80, v80
	v_exp_f32_e32 v81, v81
	v_exp_f32_e32 v82, v82
	v_exp_f32_e32 v83, v83
	v_exp_f32_e32 v84, v84
	v_exp_f32_e32 v85, v85
	v_exp_f32_e32 v86, v86
	v_exp_f32_e32 v87, v87
	v_add_f32_e32 v80, 1.0, v80
	v_add_f32_e32 v81, 1.0, v81
	v_add_f32_e32 v82, 1.0, v82
	v_add_f32_e32 v83, 1.0, v83
	v_add_f32_e32 v84, 1.0, v84
	v_add_f32_e32 v85, 1.0, v85
	v_add_f32_e32 v86, 1.0, v86
	v_add_f32_e32 v87, 1.0, v87
	v_rcp_f32_e32 v80, v80
	v_rcp_f32_e32 v81, v81
	v_rcp_f32_e32 v82, v82
	v_rcp_f32_e32 v83, v83
	v_rcp_f32_e32 v84, v84
	v_rcp_f32_e32 v85, v85
	v_rcp_f32_e32 v86, v86
	v_rcp_f32_e32 v87, v87
	v_mul_f32_e32 v72, v72, v80
	v_mul_f32_e32 v73, v73, v81
	v_mul_f32_e32 v74, v74, v82
	v_mul_f32_e32 v75, v75, v83
	v_mul_f32_e32 v76, v76, v84
	v_mul_f32_e32 v77, v77, v85
	v_mul_f32_e32 v78, v78, v86
	v_mul_f32_e32 v79, v79, v87
	v_mul_f32_e32 v64, v64, v72
	v_mul_f32_e32 v65, v65, v73
	v_mul_f32_e32 v66, v66, v74
	v_mul_f32_e32 v67, v67, v75
	v_mul_f32_e32 v68, v68, v76
	v_mul_f32_e32 v69, v69, v77
	v_mul_f32_e32 v70, v70, v78
	v_mul_f32_e32 v71, v71, v79
	v_mul_f32_e32 v7, v64, v64
	v_fmac_f32_e32 v7, v65, v65
	v_fmac_f32_e32 v7, v66, v66
	v_fmac_f32_e32 v7, v67, v67
	v_fmac_f32_e32 v7, v68, v68
	v_fmac_f32_e32 v7, v69, v69
	v_fmac_f32_e32 v7, v70, v70
	v_fmac_f32_e32 v7, v71, v71
	s_nop 1
	v_add_f32_dpp v7, v7, v7 quad_perm:[1,0,3,2] row_mask:0xf bank_mask:0xf
	s_nop 1
	v_add_f32_dpp v7, v7, v7 quad_perm:[2,3,0,1] row_mask:0xf bank_mask:0xf
	s_nop 1
	v_add_f32_dpp v7, v7, v7 row_half_mirror row_mask:0xf bank_mask:0xf
	s_nop 1
	v_add_f32_dpp v7, v7, v7 row_mirror row_mask:0xf bank_mask:0xf
	s_nop 1
	ds_bpermute_b32 v8, v5, v7
	s_waitcnt lgkmcnt(0)
	v_add_f32_e32 v7, v7, v8
	v_mov_b32_e32 v8, 0x358637bd
	v_fmac_f32_e32 v8, 0x3b800000, v7
	v_rsq_f32_e32 v8, v8
	s_nop 0
	v_mul_f32_e32 v64, v64, v8
	v_mul_f32_e32 v65, v65, v8
	v_mul_f32_e32 v66, v66, v8
	v_mul_f32_e32 v67, v67, v8
	v_mul_f32_e32 v68, v68, v8
	v_mul_f32_e32 v69, v69, v8
	v_mul_f32_e32 v70, v70, v8
	v_mul_f32_e32 v71, v71, v8
	v_mul_f32_e32 v64, v64, v16
	v_mul_f32_e32 v65, v65, v17
	v_mul_f32_e32 v66, v66, v18
	v_mul_f32_e32 v67, v67, v19
	v_mul_f32_e32 v68, v68, v20
	v_mul_f32_e32 v69, v69, v21
	v_mul_f32_e32 v70, v70, v22
	v_mul_f32_e32 v71, v71, v23
	v_cvt_pk_bf16_f32 v88, v64, v65
	v_cvt_pk_bf16_f32 v89, v66, v67
	v_cvt_pk_bf16_f32 v90, v68, v69
	v_cvt_pk_bf16_f32 v91, v70, v71
	s_nop 0
	global_store_dwordx4 v4, v[88:91], s[82:83] offset:512
	s_add_i32 s28, s27, 3
	s_cmp_lt_u32 s28, s26
	s_cselect_b32 s28, s28, 0
	s_cmp_ge_u32 s28, s23
	s_addc_u32 s44, s28, 0
	s_cmp_ge_u32 s44, s25
	s_addc_u32 s44, s44, 0
	s_lshl_b32 s44, s44, 11
	s_add_i32 s44, s44, s19
	s_lshl_b32 s16, s44, 10
	s_lshl_b32 s17, s44, 11
	s_add_u32 s30, s96, s16
	s_addc_u32 s31, s97, 0
	s_add_u32 s48, s30, 0x3600000
	s_addc_u32 s49, s31, 0
	s_add_u32 s30, s30, 0x5a00000
	s_addc_u32 s31, s31, 0
	s_add_u32 s38, s30, 0x2400000
	s_addc_u32 s39, s31, 0
	s_add_u32 s66, s96, s17
	s_addc_u32 s67, s97, 0
	s_add_u32 s66, s66, 0xea00000
	s_addc_u32 s67, s67, 0
	s_add_u32 s82, s6, s17
	s_addc_u32 s83, s7, 0
	global_load_dwordx4 v[48:51], v4, s[30:31]
	global_load_dwordx4 v[52:55], v4, s[38:39]
	global_load_dwordx4 v[56:59], v4, s[66:67]
	global_load_dwordx4 v[60:63], v4, s[48:49]
	s_add_i32 s27, s27, 2
	s_cmp_lt_u32 s27, s26
	s_cbranch_scc1 .Lcmb_top
; DI u16 f2bf(float x) { u32 u = __float_as_uint(x); u += 0x7fffu + ((u >> 16) & 1u); return (u16)(u >> 16); }
; DI float bf2f(u16 v) { return __uint_as_float(((u32)v) << 16); }
; DI void hyena_item_lat(const Params& p, int l, int it) {
;     ...
;   const int b = l16;
; #pragma unroll
;   for (int i = 0; i < 8; ++i)
; #pragma unroll
;     for (int r = 0; r < 4; ++r) {
;       const int t = tt0 + 16 * i + kg * 4 + r;
;       const size_t row = (size_t)b * TPB + posoff + t;
;       const float uu = bf2f(UT[((size_t)(c * 16 + b)) * TPB + posoff + t]);
;       const float x1 = bf2f(X1C[row * 256 + c]);
;       YM[row * 1024 + c] = f2bf(x1 * (scale * acc[i][r] + bias * uu));
;     }
	s_waitcnt vmcnt(0)
	v_readlane_b32 s19, v253, 0
	v_lshrrev_b32_e32 v4, 2, v218
	v_and_b32_e32 v5, 3, v218
	v_lshlrev_b32_e32 v6, 17, v4
	v_lshl_add_u32 v6, v5, 6, v6
	v_mul_u32_u24_e32 v7, 4352, v5
	v_lshl_add_u32 v7, v4, 2, v7
	v_mul_u32_u24_e32 v8, 272, v4
	v_lshl_add_u32 v8, v5, 6, v8
	v_lshlrev_b32_e32 v9, 9, v4
	v_lshl_add_u32 v9, v5, 5, v9
	v_lshlrev_b32_e32 v10, 11, v4
	v_lshl_add_u32 v10, v5, 5, v10
	v_lshlrev_b32_e32 v12, 14, v4
	v_lshl_add_u32 v12, v5, 6, v12
	s_mov_b32 s16, s19
	s_and_b32 s22, s16, 3
	s_bfe_u32 s23, s16, 0x50002
	s_lshr_b32 s25, s16, 7
	s_lshl_b32 s17, s22, 23
	s_lshl_b32 s16, s25, 13
	s_add_i32 s17, s17, s16
	s_lshl_b32 s16, s23, 8
	s_add_i32 s17, s17, s16
	s_add_u32 s26, s96, s17
	s_addc_u32 s27, s97, 0
	s_mul_i32 s17, s25, 0x900
	s_lshl_b32 s16, s23, 6
	s_add_i32 s17, s17, s16
	s_addk_i32 s17, 0x100
	s_lshl_b32 s16, s17, 9
	s_lshl_b32 s39, s22, 7
	s_add_i32 s16, s16, s39
	s_add_u32 s28, s96, 0x16800000
	s_addc_u32 s29, s97, 0
	s_add_u32 s28, s28, s16
	s_addc_u32 s29, s29, 0
	s_lshl_b32 s16, s17, 11
	s_add_i32 s16, s16, s39
	s_add_u32 s30, s6, s16
	s_addc_u32 s31, s7, 0
	global_load_dwordx4 v[16:19], v6, s[26:27]
	global_load_dwordx4 v[20:23], v6, s[26:27] offset:16
	global_load_dwordx4 v[24:27], v6, s[26:27] offset:32
	global_load_dwordx4 v[28:31], v6, s[26:27] offset:48
	global_load_dwordx4 v[32:35], v9, s[28:29]
	global_load_dwordx4 v[36:39], v9, s[28:29] offset:16
	s_add_i32 s16, s19, 0x200
	s_and_b32 s22, s16, 3
	s_bfe_u32 s23, s16, 0x50002
	s_lshr_b32 s25, s16, 7
	s_lshl_b32 s17, s22, 23
	s_lshl_b32 s16, s25, 13
	s_add_i32 s17, s17, s16
	s_lshl_b32 s16, s23, 8
	s_add_i32 s17, s17, s16
	s_add_u32 s48, s96, s17
	s_addc_u32 s49, s97, 0
	s_mul_i32 s17, s25, 0x900
	s_lshl_b32 s16, s23, 6
	s_add_i32 s17, s17, s16
	s_addk_i32 s17, 0x100
	s_lshl_b32 s16, s17, 9
	s_lshl_b32 s39, s22, 7
	s_add_i32 s16, s16, s39
	s_add_u32 s50, s96, 0x16800000
	s_addc_u32 s51, s97, 0
	s_add_u32 s50, s50, s16
	s_addc_u32 s51, s51, 0
	s_lshl_b32 s16, s17, 11
	s_add_i32 s16, s16, s39
	s_add_u32 s56, s6, s16
	s_addc_u32 s57, s7, 0
	global_load_dwordx4 v[40:43], v6, s[48:49]
	global_load_dwordx4 v[44:47], v6, s[48:49] offset:16
	global_load_dwordx4 v[48:51], v6, s[48:49] offset:32
	global_load_dwordx4 v[52:55], v6, s[48:49] offset:48
	global_load_dwordx4 v[56:59], v9, s[50:51]
	global_load_dwordx4 v[60:63], v9, s[50:51] offset:16
	s_waitcnt vmcnt(8)
	ds_write_b32 v7, v16
	ds_write_b32 v7, v17 offset:272
	ds_write_b32 v7, v18 offset:544
	ds_write_b32 v7, v19 offset:816
	ds_write_b32 v7, v20 offset:1088
	ds_write_b32 v7, v21 offset:1360
	ds_write_b32 v7, v22 offset:1632
	ds_write_b32 v7, v23 offset:1904
	ds_write_b32 v7, v24 offset:2176
	ds_write_b32 v7, v25 offset:2448
	ds_write_b32 v7, v26 offset:2720
	ds_write_b32 v7, v27 offset:2992
	ds_write_b32 v7, v28 offset:3264
	ds_write_b32 v7, v29 offset:3536
	ds_write_b32 v7, v30 offset:3808
	ds_write_b32 v7, v31 offset:4080
	s_waitcnt lgkmcnt(0)
	s_barrier
	ds_read_b128 v[16:19], v8
	ds_read_b128 v[20:23], v8 offset:16
	ds_read_b128 v[24:27], v8 offset:32
	ds_read_b128 v[28:31], v8 offset:48
	s_waitcnt vmcnt(6) lgkmcnt(0)
	v_lshlrev_b32_e32 v11, 16, v32
	v_mul_f32_e32 v16, v16, v11
	v_and_b32_e32 v11, 0xffff0000, v32
	v_mul_f32_e32 v17, v17, v11
	v_lshlrev_b32_e32 v11, 16, v33
	v_mul_f32_e32 v18, v18, v11
	v_and_b32_e32 v11, 0xffff0000, v33
	v_mul_f32_e32 v19, v19, v11
	v_lshlrev_b32_e32 v11, 16, v34
	v_mul_f32_e32 v20, v20, v11
	v_and_b32_e32 v11, 0xffff0000, v34
	v_mul_f32_e32 v21, v21, v11
	v_lshlrev_b32_e32 v11, 16, v35
	v_mul_f32_e32 v22, v22, v11
	v_and_b32_e32 v11, 0xffff0000, v35
	v_mul_f32_e32 v23, v23, v11
	v_lshlrev_b32_e32 v11, 16, v36
	v_mul_f32_e32 v24, v24, v11
	v_and_b32_e32 v11, 0xffff0000, v36
	v_mul_f32_e32 v25, v25, v11
	v_lshlrev_b32_e32 v11, 16, v37
	v_mul_f32_e32 v26, v26, v11
	v_and_b32_e32 v11, 0xffff0000, v37
	v_mul_f32_e32 v27, v27, v11
	v_lshlrev_b32_e32 v11, 16, v38
	v_mul_f32_e32 v28, v28, v11
	v_and_b32_e32 v11, 0xffff0000, v38
	v_mul_f32_e32 v29, v29, v11
	v_lshlrev_b32_e32 v11, 16, v39
	v_mul_f32_e32 v30, v30, v11
	v_and_b32_e32 v11, 0xffff0000, v39
	v_mul_f32_e32 v31, v31, v11
	v_cvt_pk_bf16_f32 v32, v16, v17
	v_cvt_pk_bf16_f32 v33, v18, v19
	v_cvt_pk_bf16_f32 v34, v20, v21
	v_cvt_pk_bf16_f32 v35, v22, v23
	v_cvt_pk_bf16_f32 v36, v24, v25
	v_cvt_pk_bf16_f32 v37, v26, v27
	v_cvt_pk_bf16_f32 v38, v28, v29
	v_cvt_pk_bf16_f32 v39, v30, v31
	s_nop 0
	global_store_dwordx4 v10, v[32:35], s[30:31]
	global_store_dwordx4 v10, v[36:39], s[30:31] offset:16
	s_barrier
	s_add_i32 s16, s19, 0x400
	s_and_b32 s22, s16, 3
	s_bfe_u32 s23, s16, 0x50002
	s_lshr_b32 s25, s16, 7
	s_lshl_b32 s17, s22, 23
	s_lshl_b32 s16, s25, 13
	s_add_i32 s17, s17, s16
	s_lshl_b32 s16, s23, 8
	s_add_i32 s17, s17, s16
	s_add_u32 s26, s96, s17
	s_addc_u32 s27, s97, 0
	s_mul_i32 s17, s25, 0x900
	s_lshl_b32 s16, s23, 6
	s_add_i32 s17, s17, s16
	s_addk_i32 s17, 0x100
	s_lshl_b32 s16, s17, 9
	s_lshl_b32 s39, s22, 7
	s_add_i32 s16, s16, s39
	s_add_u32 s28, s96, 0x16800000
	s_addc_u32 s29, s97, 0
	s_add_u32 s28, s28, s16
	s_addc_u32 s29, s29, 0
	s_lshl_b32 s16, s17, 11
	s_add_i32 s16, s16, s39
	s_add_u32 s30, s6, s16
	s_addc_u32 s31, s7, 0
	global_load_dwordx4 v[16:19], v6, s[26:27]
	global_load_dwordx4 v[20:23], v6, s[26:27] offset:16
	global_load_dwordx4 v[24:27], v6, s[26:27] offset:32
	global_load_dwordx4 v[28:31], v6, s[26:27] offset:48
	global_load_dwordx4 v[32:35], v9, s[28:29]
	global_load_dwordx4 v[36:39], v9, s[28:29] offset:16
	s_waitcnt vmcnt(10)
	ds_write_b32 v7, v40
	ds_write_b32 v7, v41 offset:272
	ds_write_b32 v7, v42 offset:544
	ds_write_b32 v7, v43 offset:816
	ds_write_b32 v7, v44 offset:1088
	ds_write_b32 v7, v45 offset:1360
	ds_write_b32 v7, v46 offset:1632
	ds_write_b32 v7, v47 offset:1904
	ds_write_b32 v7, v48 offset:2176
	ds_write_b32 v7, v49 offset:2448
	ds_write_b32 v7, v50 offset:2720
	ds_write_b32 v7, v51 offset:2992
	ds_write_b32 v7, v52 offset:3264
	ds_write_b32 v7, v53 offset:3536
	ds_write_b32 v7, v54 offset:3808
	ds_write_b32 v7, v55 offset:4080
	s_waitcnt lgkmcnt(0)
	s_barrier
; DI u16 f2bf(float x) { u32 u = __float_as_uint(x); u += 0x7fffu + ((u >> 16) & 1u); return (u16)(u >> 16); }
; DI float bf2f(u16 v) { return __uint_as_float(((u32)v) << 16); }
; DI void hyena_item_lat(const Params& p, int l, int it) {
;     ...
;   const int b = l16;
; #pragma unroll
;   for (int i = 0; i < 8; ++i)
; #pragma unroll
;     for (int r = 0; r < 4; ++r) {
;       const int t = tt0 + 16 * i + kg * 4 + r;
;       const size_t row = (size_t)b * TPB + posoff + t;
;       const float uu = bf2f(UT[((size_t)(c * 16 + b)) * TPB + posoff + t]);
;       const float x1 = bf2f(X1C[row * 256 + c]);
;       YM[row * 1024 + c] = f2bf(x1 * (scale * acc[i][r] + bias * uu));
;     }
	ds_read_b128 v[40:43], v8
	ds_read_b128 v[44:47], v8 offset:16
	ds_read_b128 v[48:51], v8 offset:32
	ds_read_b128 v[52:55], v8 offset:48
	s_waitcnt vmcnt(8) lgkmcnt(0)
	v_lshlrev_b32_e32 v11, 16, v56
	v_mul_f32_e32 v40, v40, v11
	v_and_b32_e32 v11, 0xffff0000, v56
	v_mul_f32_e32 v41, v41, v11
	v_lshlrev_b32_e32 v11, 16, v57
	v_mul_f32_e32 v42, v42, v11
	v_and_b32_e32 v11, 0xffff0000, v57
	v_mul_f32_e32 v43, v43, v11
	v_lshlrev_b32_e32 v11, 16, v58
	v_mul_f32_e32 v44, v44, v11
	v_and_b32_e32 v11, 0xffff0000, v58
	v_mul_f32_e32 v45, v45, v11
	v_lshlrev_b32_e32 v11, 16, v59
	v_mul_f32_e32 v46, v46, v11
	v_and_b32_e32 v11, 0xffff0000, v59
	v_mul_f32_e32 v47, v47, v11
	v_lshlrev_b32_e32 v11, 16, v60
	v_mul_f32_e32 v48, v48, v11
	v_and_b32_e32 v11, 0xffff0000, v60
	v_mul_f32_e32 v49, v49, v11
	v_lshlrev_b32_e32 v11, 16, v61
	v_mul_f32_e32 v50, v50, v11
	v_and_b32_e32 v11, 0xffff0000, v61
	v_mul_f32_e32 v51, v51, v11
	v_lshlrev_b32_e32 v11, 16, v62
	v_mul_f32_e32 v52, v52, v11
	v_and_b32_e32 v11, 0xffff0000, v62
	v_mul_f32_e32 v53, v53, v11
	v_lshlrev_b32_e32 v11, 16, v63
	v_mul_f32_e32 v54, v54, v11
	v_and_b32_e32 v11, 0xffff0000, v63
	v_mul_f32_e32 v55, v55, v11
	v_cvt_pk_bf16_f32 v56, v40, v41
	v_cvt_pk_bf16_f32 v57, v42, v43
	v_cvt_pk_bf16_f32 v58, v44, v45
	v_cvt_pk_bf16_f32 v59, v46, v47
	v_cvt_pk_bf16_f32 v60, v48, v49
	v_cvt_pk_bf16_f32 v61, v50, v51
	v_cvt_pk_bf16_f32 v62, v52, v53
	v_cvt_pk_bf16_f32 v63, v54, v55
	s_nop 0
	global_store_dwordx4 v10, v[56:59], s[56:57]
	global_store_dwordx4 v10, v[60:63], s[56:57] offset:16
	s_barrier
	s_add_i32 s16, s19, 0x600
	s_and_b32 s22, s16, 3
	s_bfe_u32 s23, s16, 0x50002
	s_lshr_b32 s25, s16, 7
	s_lshl_b32 s17, s22, 23
	s_lshl_b32 s16, s25, 13
	s_add_i32 s17, s17, s16
	s_lshl_b32 s16, s23, 8
	s_add_i32 s17, s17, s16
	s_add_u32 s48, s96, s17
	s_addc_u32 s49, s97, 0
	s_mul_i32 s17, s25, 0x900
	s_lshl_b32 s16, s23, 6
	s_add_i32 s17, s17, s16
	s_addk_i32 s17, 0x100
	s_lshl_b32 s16, s17, 9
	s_lshl_b32 s39, s22, 7
	s_add_i32 s16, s16, s39
	s_add_u32 s50, s96, 0x16800000
	s_addc_u32 s51, s97, 0
	s_add_u32 s50, s50, s16
	s_addc_u32 s51, s51, 0
	s_lshl_b32 s16, s17, 11
	s_add_i32 s16, s16, s39
	s_add_u32 s56, s6, s16
	s_addc_u32 s57, s7, 0
	global_load_dwordx4 v[40:43], v6, s[48:49]
	global_load_dwordx4 v[44:47], v6, s[48:49] offset:16
	global_load_dwordx4 v[48:51], v6, s[48:49] offset:32
	global_load_dwordx4 v[52:55], v6, s[48:49] offset:48
	global_load_dwordx4 v[56:59], v9, s[50:51]
	global_load_dwordx4 v[60:63], v9, s[50:51] offset:16
	s_waitcnt vmcnt(10)
	ds_write_b32 v7, v16
	ds_write_b32 v7, v17 offset:272
	ds_write_b32 v7, v18 offset:544
	ds_write_b32 v7, v19 offset:816
	ds_write_b32 v7, v20 offset:1088
	ds_write_b32 v7, v21 offset:1360
	ds_write_b32 v7, v22 offset:1632
	ds_write_b32 v7, v23 offset:1904
	ds_write_b32 v7, v24 offset:2176
	ds_write_b32 v7, v25 offset:2448
	ds_write_b32 v7, v26 offset:2720
	ds_write_b32 v7, v27 offset:2992
	ds_write_b32 v7, v28 offset:3264
	ds_write_b32 v7, v29 offset:3536
	ds_write_b32 v7, v30 offset:3808
	ds_write_b32 v7, v31 offset:4080
	s_waitcnt lgkmcnt(0)
	s_barrier
	ds_read_b128 v[16:19], v8
	ds_read_b128 v[20:23], v8 offset:16
	ds_read_b128 v[24:27], v8 offset:32
	ds_read_b128 v[28:31], v8 offset:48
	s_waitcnt vmcnt(8) lgkmcnt(0)
	v_lshlrev_b32_e32 v11, 16, v32
	v_mul_f32_e32 v16, v16, v11
	v_and_b32_e32 v11, 0xffff0000, v32
	v_mul_f32_e32 v17, v17, v11
	v_lshlrev_b32_e32 v11, 16, v33
	v_mul_f32_e32 v18, v18, v11
	v_and_b32_e32 v11, 0xffff0000, v33
	v_mul_f32_e32 v19, v19, v11
	v_lshlrev_b32_e32 v11, 16, v34
	v_mul_f32_e32 v20, v20, v11
	v_and_b32_e32 v11, 0xffff0000, v34
	v_mul_f32_e32 v21, v21, v11
	v_lshlrev_b32_e32 v11, 16, v35
	v_mul_f32_e32 v22, v22, v11
	v_and_b32_e32 v11, 0xffff0000, v35
	v_mul_f32_e32 v23, v23, v11
	v_lshlrev_b32_e32 v11, 16, v36
	v_mul_f32_e32 v24, v24, v11
	v_and_b32_e32 v11, 0xffff0000, v36
	v_mul_f32_e32 v25, v25, v11
	v_lshlrev_b32_e32 v11, 16, v37
	v_mul_f32_e32 v26, v26, v11
	v_and_b32_e32 v11, 0xffff0000, v37
	v_mul_f32_e32 v27, v27, v11
	v_lshlrev_b32_e32 v11, 16, v38
	v_mul_f32_e32 v28, v28, v11
	v_and_b32_e32 v11, 0xffff0000, v38
	v_mul_f32_e32 v29, v29, v11
	v_lshlrev_b32_e32 v11, 16, v39
	v_mul_f32_e32 v30, v30, v11
	v_and_b32_e32 v11, 0xffff0000, v39
	v_mul_f32_e32 v31, v31, v11
	v_cvt_pk_bf16_f32 v32, v16, v17
	v_cvt_pk_bf16_f32 v33, v18, v19
	v_cvt_pk_bf16_f32 v34, v20, v21
	v_cvt_pk_bf16_f32 v35, v22, v23
	v_cvt_pk_bf16_f32 v36, v24, v25
	v_cvt_pk_bf16_f32 v37, v26, v27
	v_cvt_pk_bf16_f32 v38, v28, v29
	v_cvt_pk_bf16_f32 v39, v30, v31
	s_nop 0
	global_store_dwordx4 v10, v[32:35], s[30:31]
	global_store_dwordx4 v10, v[36:39], s[30:31] offset:16
	s_barrier
	s_cmpk_lt_u32 s19, 0x100
	s_cbranch_scc0 .Lhyt_last
	s_and_b32 s22, s19, 3
	s_bfe_u32 s23, s19, 0x20002
	s_lshr_b32 s25, s19, 4
	s_lshl_b32 s17, s22, 20
	s_lshl_b32 s16, s25, 10
	s_add_i32 s17, s17, s16
	s_lshl_b32 s16, s23, 8
	s_add_i32 s17, s17, s16
	s_add_u32 s17, s17, 0x2000000
	s_add_u32 s26, s96, s17
	s_addc_u32 s27, s97, 0
	s_mul_i32 s17, s25, 0x900
	s_lshl_b32 s16, s23, 6
	s_add_i32 s17, s17, s16
	s_lshl_b32 s16, s17, 9
	s_lshl_b32 s39, s22, 7
	s_add_i32 s16, s16, s39
	s_add_u32 s28, s96, 0x16800000
	s_addc_u32 s29, s97, 0
	s_add_u32 s28, s28, s16
	s_addc_u32 s29, s29, 0
	s_lshl_b32 s16, s17, 11
	s_add_i32 s16, s16, s39
	s_add_u32 s30, s6, s16
	s_addc_u32 s31, s7, 0
	global_load_dwordx4 v[16:19], v12, s[26:27]
	global_load_dwordx4 v[20:23], v12, s[26:27] offset:16
	global_load_dwordx4 v[24:27], v12, s[26:27] offset:32
	global_load_dwordx4 v[28:31], v12, s[26:27] offset:48
	global_load_dwordx4 v[32:35], v9, s[28:29]
	global_load_dwordx4 v[36:39], v9, s[28:29] offset:16
	s_waitcnt vmcnt(10)
	ds_write_b32 v7, v40
	ds_write_b32 v7, v41 offset:272
	ds_write_b32 v7, v42 offset:544
	ds_write_b32 v7, v43 offset:816
	ds_write_b32 v7, v44 offset:1088
	ds_write_b32 v7, v45 offset:1360
	ds_write_b32 v7, v46 offset:1632
	ds_write_b32 v7, v47 offset:1904
	ds_write_b32 v7, v48 offset:2176
	ds_write_b32 v7, v49 offset:2448
	ds_write_b32 v7, v50 offset:2720
	ds_write_b32 v7, v51 offset:2992
	ds_write_b32 v7, v52 offset:3264
	ds_write_b32 v7, v53 offset:3536
	ds_write_b32 v7, v54 offset:3808
	ds_write_b32 v7, v55 offset:4080
	s_waitcnt lgkmcnt(0)
	s_barrier
; DI u16 f2bf(float x) { u32 u = __float_as_uint(x); u += 0x7fffu + ((u >> 16) & 1u); return (u16)(u >> 16); }
; DI float bf2f(u16 v) { return __uint_as_float(((u32)v) << 16); }
; DI void hyena_item_lat(const Params& p, int l, int it) {
;     ...
;   const int b = l16;
; #pragma unroll
;   for (int i = 0; i < 8; ++i)
; #pragma unroll
;     for (int r = 0; r < 4; ++r) {
;       const int t = tt0 + 16 * i + kg * 4 + r;
;       const size_t row = (size_t)b * TPB + posoff + t;
;       const float uu = bf2f(UT[((size_t)(c * 16 + b)) * TPB + posoff + t]);
;       const float x1 = bf2f(X1C[row * 256 + c]);
;       YM[row * 1024 + c] = f2bf(x1 * (scale * acc[i][r] + bias * uu));
;     }
	ds_read_b128 v[40:43], v8
	ds_read_b128 v[44:47], v8 offset:16
	ds_read_b128 v[48:51], v8 offset:32
	ds_read_b128 v[52:55], v8 offset:48
	s_waitcnt vmcnt(8) lgkmcnt(0)
	v_lshlrev_b32_e32 v11, 16, v56
	v_mul_f32_e32 v40, v40, v11
	v_and_b32_e32 v11, 0xffff0000, v56
	v_mul_f32_e32 v41, v41, v11
	v_lshlrev_b32_e32 v11, 16, v57
	v_mul_f32_e32 v42, v42, v11
	v_and_b32_e32 v11, 0xffff0000, v57
	v_mul_f32_e32 v43, v43, v11
	v_lshlrev_b32_e32 v11, 16, v58
	v_mul_f32_e32 v44, v44, v11
	v_and_b32_e32 v11, 0xffff0000, v58
	v_mul_f32_e32 v45, v45, v11
	v_lshlrev_b32_e32 v11, 16, v59
	v_mul_f32_e32 v46, v46, v11
	v_and_b32_e32 v11, 0xffff0000, v59
	v_mul_f32_e32 v47, v47, v11
	v_lshlrev_b32_e32 v11, 16, v60
	v_mul_f32_e32 v48, v48, v11
	v_and_b32_e32 v11, 0xffff0000, v60
	v_mul_f32_e32 v49, v49, v11
	v_lshlrev_b32_e32 v11, 16, v61
	v_mul_f32_e32 v50, v50, v11
	v_and_b32_e32 v11, 0xffff0000, v61
	v_mul_f32_e32 v51, v51, v11
	v_lshlrev_b32_e32 v11, 16, v62
	v_mul_f32_e32 v52, v52, v11
	v_and_b32_e32 v11, 0xffff0000, v62
	v_mul_f32_e32 v53, v53, v11
	v_lshlrev_b32_e32 v11, 16, v63
	v_mul_f32_e32 v54, v54, v11
	v_and_b32_e32 v11, 0xffff0000, v63
	v_mul_f32_e32 v55, v55, v11
	v_cvt_pk_bf16_f32 v56, v40, v41
	v_cvt_pk_bf16_f32 v57, v42, v43
	v_cvt_pk_bf16_f32 v58, v44, v45
	v_cvt_pk_bf16_f32 v59, v46, v47
	v_cvt_pk_bf16_f32 v60, v48, v49
	v_cvt_pk_bf16_f32 v61, v50, v51
	v_cvt_pk_bf16_f32 v62, v52, v53
	v_cvt_pk_bf16_f32 v63, v54, v55
	s_nop 0
	global_store_dwordx4 v10, v[56:59], s[56:57]
	global_store_dwordx4 v10, v[60:63], s[56:57] offset:16
	s_barrier
	s_waitcnt vmcnt(4)
	ds_write_b32 v7, v16
	ds_write_b32 v7, v17 offset:272
	ds_write_b32 v7, v18 offset:544
	ds_write_b32 v7, v19 offset:816
	ds_write_b32 v7, v20 offset:1088
	ds_write_b32 v7, v21 offset:1360
	ds_write_b32 v7, v22 offset:1632
	ds_write_b32 v7, v23 offset:1904
	ds_write_b32 v7, v24 offset:2176
	ds_write_b32 v7, v25 offset:2448
	ds_write_b32 v7, v26 offset:2720
	ds_write_b32 v7, v27 offset:2992
	ds_write_b32 v7, v28 offset:3264
	ds_write_b32 v7, v29 offset:3536
	ds_write_b32 v7, v30 offset:3808
	ds_write_b32 v7, v31 offset:4080
	s_waitcnt lgkmcnt(0)
	s_barrier
	ds_read_b128 v[16:19], v8
	ds_read_b128 v[20:23], v8 offset:16
	ds_read_b128 v[24:27], v8 offset:32
	ds_read_b128 v[28:31], v8 offset:48
	s_waitcnt vmcnt(2) lgkmcnt(0)
	v_lshlrev_b32_e32 v11, 16, v32
	v_mul_f32_e32 v16, v16, v11
	v_and_b32_e32 v11, 0xffff0000, v32
	v_mul_f32_e32 v17, v17, v11
	v_lshlrev_b32_e32 v11, 16, v33
	v_mul_f32_e32 v18, v18, v11
	v_and_b32_e32 v11, 0xffff0000, v33
	v_mul_f32_e32 v19, v19, v11
	v_lshlrev_b32_e32 v11, 16, v34
	v_mul_f32_e32 v20, v20, v11
	v_and_b32_e32 v11, 0xffff0000, v34
	v_mul_f32_e32 v21, v21, v11
	v_lshlrev_b32_e32 v11, 16, v35
	v_mul_f32_e32 v22, v22, v11
	v_and_b32_e32 v11, 0xffff0000, v35
	v_mul_f32_e32 v23, v23, v11
	v_lshlrev_b32_e32 v11, 16, v36
	v_mul_f32_e32 v24, v24, v11
	v_and_b32_e32 v11, 0xffff0000, v36
	v_mul_f32_e32 v25, v25, v11
	v_lshlrev_b32_e32 v11, 16, v37
	v_mul_f32_e32 v26, v26, v11
	v_and_b32_e32 v11, 0xffff0000, v37
	v_mul_f32_e32 v27, v27, v11
	v_lshlrev_b32_e32 v11, 16, v38
	v_mul_f32_e32 v28, v28, v11
	v_and_b32_e32 v11, 0xffff0000, v38
	v_mul_f32_e32 v29, v29, v11
	v_lshlrev_b32_e32 v11, 16, v39
	v_mul_f32_e32 v30, v30, v11
	v_and_b32_e32 v11, 0xffff0000, v39
	v_mul_f32_e32 v31, v31, v11
	v_cvt_pk_bf16_f32 v32, v16, v17
	v_cvt_pk_bf16_f32 v33, v18, v19
	v_cvt_pk_bf16_f32 v34, v20, v21
	v_cvt_pk_bf16_f32 v35, v22, v23
	v_cvt_pk_bf16_f32 v36, v24, v25
	v_cvt_pk_bf16_f32 v37, v26, v27
	v_cvt_pk_bf16_f32 v38, v28, v29
	v_cvt_pk_bf16_f32 v39, v30, v31
	s_nop 0
	global_store_dwordx4 v10, v[32:35], s[30:31]
	global_store_dwordx4 v10, v[36:39], s[30:31] offset:16
	s_barrier
	s_branch .Lhyt_done
.Lhyt_last:
	s_waitcnt vmcnt(4)
	ds_write_b32 v7, v40
	ds_write_b32 v7, v41 offset:272
	ds_write_b32 v7, v42 offset:544
	ds_write_b32 v7, v43 offset:816
	ds_write_b32 v7, v44 offset:1088
	ds_write_b32 v7, v45 offset:1360
	ds_write_b32 v7, v46 offset:1632
	ds_write_b32 v7, v47 offset:1904
	ds_write_b32 v7, v48 offset:2176
	ds_write_b32 v7, v49 offset:2448
	ds_write_b32 v7, v50 offset:2720
	ds_write_b32 v7, v51 offset:2992
	ds_write_b32 v7, v52 offset:3264
	ds_write_b32 v7, v53 offset:3536
	ds_write_b32 v7, v54 offset:3808
	ds_write_b32 v7, v55 offset:4080
	s_waitcnt lgkmcnt(0)
	s_barrier
	ds_read_b128 v[40:43], v8
	ds_read_b128 v[44:47], v8 offset:16
	ds_read_b128 v[48:51], v8 offset:32
	ds_read_b128 v[52:55], v8 offset:48
	s_waitcnt vmcnt(2) lgkmcnt(0)
	v_lshlrev_b32_e32 v11, 16, v56
	v_mul_f32_e32 v40, v40, v11
	v_and_b32_e32 v11, 0xffff0000, v56
	v_mul_f32_e32 v41, v41, v11
	v_lshlrev_b32_e32 v11, 16, v57
	v_mul_f32_e32 v42, v42, v11
	v_and_b32_e32 v11, 0xffff0000, v57
	v_mul_f32_e32 v43, v43, v11
	v_lshlrev_b32_e32 v11, 16, v58
	v_mul_f32_e32 v44, v44, v11
	v_and_b32_e32 v11, 0xffff0000, v58
	v_mul_f32_e32 v45, v45, v11
	v_lshlrev_b32_e32 v11, 16, v59
	v_mul_f32_e32 v46, v46, v11
	v_and_b32_e32 v11, 0xffff0000, v59
	v_mul_f32_e32 v47, v47, v11
	v_lshlrev_b32_e32 v11, 16, v60
	v_mul_f32_e32 v48, v48, v11
	v_and_b32_e32 v11, 0xffff0000, v60
	v_mul_f32_e32 v49, v49, v11
	v_lshlrev_b32_e32 v11, 16, v61
	v_mul_f32_e32 v50, v50, v11
	v_and_b32_e32 v11, 0xffff0000, v61
	v_mul_f32_e32 v51, v51, v11
	v_lshlrev_b32_e32 v11, 16, v62
	v_mul_f32_e32 v52, v52, v11
	v_and_b32_e32 v11, 0xffff0000, v62
	v_mul_f32_e32 v53, v53, v11
	v_lshlrev_b32_e32 v11, 16, v63
	v_mul_f32_e32 v54, v54, v11
	v_and_b32_e32 v11, 0xffff0000, v63
	v_mul_f32_e32 v55, v55, v11
	v_cvt_pk_bf16_f32 v56, v40, v41
	v_cvt_pk_bf16_f32 v57, v42, v43
	v_cvt_pk_bf16_f32 v58, v44, v45
	v_cvt_pk_bf16_f32 v59, v46, v47
	v_cvt_pk_bf16_f32 v60, v48, v49
	v_cvt_pk_bf16_f32 v61, v50, v51
	v_cvt_pk_bf16_f32 v62, v52, v53
	v_cvt_pk_bf16_f32 v63, v54, v55
	s_nop 0
	global_store_dwordx4 v10, v[56:59], s[56:57]
	global_store_dwordx4 v10, v[60:63], s[56:57] offset:16
	s_barrier
.Lhyt_done:
	s_waitcnt vmcnt(0)
.LBB0_1208:
	s_or_b64 exec, exec, s[36:37]
	s_waitcnt vmcnt(0)
	s_barrier
	s_mov_b64 s[0:1], exec
	v_readlane_b32 s34, v253, 1
	v_readlane_b32 s35, v253, 2
	s_and_b64 s[34:35], s[0:1], s[34:35]
	s_mov_b64 exec, s[34:35]
	s_cbranch_execz .LBB0_1260
	v_readlane_b32 s13, v255, 62
	s_waitcnt vmcnt(0) expcnt(0) lgkmcnt(0)
	s_nop 0
	v_mov_b32_e32 v0, s13
	ds_read_b32 v2, v0
	v_readlane_b32 s13, v255, 63
	s_waitcnt lgkmcnt(0)
	v_cmp_ne_u32_e32 vcc, 0, v2
	v_mov_b32_e32 v0, s13
	ds_read_b32 v0, v0
	s_cbranch_vccnz .LBB0_1224
	s_mov_b32 s13, 1
	s_branch .LBB0_1212
